# h3 second ao loop (triangular, exec-masked): software-pipelined 2x with a second register set so next iteration LDS reads overlap the pk_fma block
# baseline (speedup 1.0000x reference)
; DI void hgrn_h3(const Params& p, int l, int item, char* lds) {
;     ...
;   for (int s4 = 0; s4 <= tblk; ++s4) {
;     float a[4][4], sv[4][4];
; #pragma unroll
;     for (int i = 0; i < 4; ++i) { const f32x4 x = *(const f32x4*)(LK + (4 * tblk + i) * HP + 4 * s4); a[i][0] = x.x; a[i][1] = x.y; a[i][2] = x.z; a[i][3] = x.w; }
; #pragma unroll
;     for (int dd = 0; dd < 4; ++dd) { const f32x4 x = *(const f32x4*)(V + (4 * s4 + dd) * HP + 4 * eblk); sv[dd][0] = x.x; sv[dd][1] = x.y; sv[dd][2] = x.z; sv[dd][3] = x.w; }
; #pragma unroll
;     for (int i = 0; i < 4; ++i)
; #pragma unroll
;       for (int dd = 0; dd < 4; ++dd)
; #pragma unroll
;         for (int j = 0; j < 4; ++j) ao[i][j] += a[i][dd] * sv[dd][j];
;   }
.Lao2_loop:
	s_waitcnt lgkmcnt(0)
	ds_read_b128 v[76:79], v3 offset:16
	ds_read_b128 v[80:83], v3 offset:288
	ds_read_b128 v[84:87], v3 offset:560
	ds_read_b128 v[88:91], v3 offset:832
	ds_read_b128 v[92:95], v4 offset:1088
	ds_read_b128 v[96:99], v4 offset:1360
	ds_read_b128 v[100:103], v4 offset:1632
	ds_read_b128 v[104:107], v4 offset:1904
	v_mov_b32_e32 v20, v35
	v_pk_fma_f32 v[16:17], v[32:33], v[54:55], v[28:29] op_sel_hi:[0,1,1]
	v_pk_fma_f32 v[16:17], v[32:33], v[58:59], v[16:17] op_sel:[1,0,0]
	v_pk_fma_f32 v[12:13], v[40:41], v[54:55], v[12:13] op_sel_hi:[0,1,1]
	v_pk_fma_f32 v[16:17], v[34:35], v[62:63], v[16:17] op_sel_hi:[0,1,1]
	v_pk_fma_f32 v[28:29], v[20:21], v[66:67], v[16:17] op_sel_hi:[0,1,1]
	v_pk_fma_f32 v[16:17], v[32:33], v[56:57], v[26:27] op_sel_hi:[0,1,1]
	v_pk_fma_f32 v[16:17], v[32:33], v[60:61], v[16:17] op_sel:[1,0,0]
	v_pk_fma_f32 v[10:11], v[40:41], v[56:57], v[10:11] op_sel_hi:[0,1,1]
	v_pk_fma_f32 v[16:17], v[34:35], v[64:65], v[16:17] op_sel_hi:[0,1,1]
	v_pk_fma_f32 v[26:27], v[20:21], v[68:69], v[16:17] op_sel_hi:[0,1,1]
	v_pk_fma_f32 v[16:17], v[36:37], v[54:55], v[22:23] op_sel_hi:[0,1,1]
	v_pk_fma_f32 v[16:17], v[36:37], v[58:59], v[16:17] op_sel:[1,0,0]
	v_mov_b32_e32 v20, v39
	v_pk_fma_f32 v[16:17], v[38:39], v[62:63], v[16:17] op_sel_hi:[0,1,1]
	v_pk_fma_f32 v[22:23], v[20:21], v[66:67], v[16:17] op_sel_hi:[0,1,1]
	v_pk_fma_f32 v[16:17], v[36:37], v[56:57], v[18:19] op_sel_hi:[0,1,1]
	v_pk_fma_f32 v[16:17], v[36:37], v[60:61], v[16:17] op_sel:[1,0,0]
	v_pk_fma_f32 v[12:13], v[40:41], v[58:59], v[12:13] op_sel:[1,0,0]
	v_pk_fma_f32 v[16:17], v[38:39], v[64:65], v[16:17] op_sel_hi:[0,1,1]
	v_pk_fma_f32 v[10:11], v[40:41], v[60:61], v[10:11] op_sel:[1,0,0]
	v_pk_fma_f32 v[8:9], v[50:51], v[54:55], v[8:9] op_sel_hi:[0,1,1]
	v_pk_fma_f32 v[6:7], v[50:51], v[56:57], v[6:7] op_sel_hi:[0,1,1]
	v_pk_fma_f32 v[18:19], v[20:21], v[68:69], v[16:17] op_sel_hi:[0,1,1]
	v_pk_fma_f32 v[12:13], v[42:43], v[62:63], v[12:13] op_sel_hi:[0,1,1]
	v_mov_b32_e32 v16, v43
	v_pk_fma_f32 v[10:11], v[42:43], v[64:65], v[10:11] op_sel_hi:[0,1,1]
	v_pk_fma_f32 v[8:9], v[50:51], v[58:59], v[8:9] op_sel:[1,0,0]
	v_pk_fma_f32 v[6:7], v[50:51], v[60:61], v[6:7] op_sel:[1,0,0]
	v_add_u32_e32 v5, -1, v5
	v_pk_fma_f32 v[12:13], v[16:17], v[66:67], v[12:13] op_sel_hi:[0,1,1]
	v_pk_fma_f32 v[10:11], v[16:17], v[68:69], v[10:11] op_sel_hi:[0,1,1]
	v_pk_fma_f32 v[8:9], v[52:53], v[62:63], v[8:9] op_sel_hi:[0,1,1]
	v_mov_b32_e32 v16, v53
	v_pk_fma_f32 v[6:7], v[52:53], v[64:65], v[6:7] op_sel_hi:[0,1,1]
	v_cmp_eq_u32_e32 vcc, 0, v5
	v_pk_fma_f32 v[8:9], v[16:17], v[66:67], v[8:9] op_sel_hi:[0,1,1]
	v_pk_fma_f32 v[6:7], v[16:17], v[68:69], v[6:7] op_sel_hi:[0,1,1]
	s_or_b64 s[0:1], vcc, s[0:1]
	s_andn2_b64 exec, exec, s[0:1]
	s_cbranch_execz .Lao2_done
	s_waitcnt lgkmcnt(0)
	ds_read_b128 v[32:35], v3 offset:32
	ds_read_b128 v[36:39], v3 offset:304
	ds_read_b128 v[40:43], v3 offset:576
	ds_read_b128 v[50:53], v3 offset:848
	ds_read_b128 v[54:57], v4 offset:2176
	ds_read_b128 v[58:61], v4 offset:2448
	ds_read_b128 v[62:65], v4 offset:2720
	ds_read_b128 v[66:69], v4 offset:2992
	v_mov_b32_e32 v20, v79
	v_pk_fma_f32 v[16:17], v[76:77], v[92:93], v[28:29] op_sel_hi:[0,1,1]
	v_pk_fma_f32 v[16:17], v[76:77], v[96:97], v[16:17] op_sel:[1,0,0]
	v_pk_fma_f32 v[12:13], v[84:85], v[92:93], v[12:13] op_sel_hi:[0,1,1]
	v_pk_fma_f32 v[16:17], v[78:79], v[100:101], v[16:17] op_sel_hi:[0,1,1]
	v_pk_fma_f32 v[28:29], v[20:21], v[104:105], v[16:17] op_sel_hi:[0,1,1]
	v_pk_fma_f32 v[16:17], v[76:77], v[94:95], v[26:27] op_sel_hi:[0,1,1]
	v_pk_fma_f32 v[16:17], v[76:77], v[98:99], v[16:17] op_sel:[1,0,0]
	v_pk_fma_f32 v[10:11], v[84:85], v[94:95], v[10:11] op_sel_hi:[0,1,1]
	v_pk_fma_f32 v[16:17], v[78:79], v[102:103], v[16:17] op_sel_hi:[0,1,1]
	v_pk_fma_f32 v[26:27], v[20:21], v[106:107], v[16:17] op_sel_hi:[0,1,1]
	v_pk_fma_f32 v[16:17], v[80:81], v[92:93], v[22:23] op_sel_hi:[0,1,1]
	v_pk_fma_f32 v[16:17], v[80:81], v[96:97], v[16:17] op_sel:[1,0,0]
	v_mov_b32_e32 v20, v83
	v_pk_fma_f32 v[16:17], v[82:83], v[100:101], v[16:17] op_sel_hi:[0,1,1]
	v_pk_fma_f32 v[22:23], v[20:21], v[104:105], v[16:17] op_sel_hi:[0,1,1]
	v_pk_fma_f32 v[16:17], v[80:81], v[94:95], v[18:19] op_sel_hi:[0,1,1]
	v_pk_fma_f32 v[16:17], v[80:81], v[98:99], v[16:17] op_sel:[1,0,0]
	v_pk_fma_f32 v[12:13], v[84:85], v[96:97], v[12:13] op_sel:[1,0,0]
	v_pk_fma_f32 v[16:17], v[82:83], v[102:103], v[16:17] op_sel_hi:[0,1,1]
	v_pk_fma_f32 v[10:11], v[84:85], v[98:99], v[10:11] op_sel:[1,0,0]
	v_pk_fma_f32 v[8:9], v[88:89], v[92:93], v[8:9] op_sel_hi:[0,1,1]
	v_pk_fma_f32 v[6:7], v[88:89], v[94:95], v[6:7] op_sel_hi:[0,1,1]
	v_pk_fma_f32 v[18:19], v[20:21], v[106:107], v[16:17] op_sel_hi:[0,1,1]
	v_pk_fma_f32 v[12:13], v[86:87], v[100:101], v[12:13] op_sel_hi:[0,1,1]
	v_mov_b32_e32 v16, v87
	v_pk_fma_f32 v[10:11], v[86:87], v[102:103], v[10:11] op_sel_hi:[0,1,1]
	v_pk_fma_f32 v[8:9], v[88:89], v[96:97], v[8:9] op_sel:[1,0,0]
	v_pk_fma_f32 v[6:7], v[88:89], v[98:99], v[6:7] op_sel:[1,0,0]
	v_add_u32_e32 v5, -1, v5
	v_pk_fma_f32 v[12:13], v[16:17], v[104:105], v[12:13] op_sel_hi:[0,1,1]
	v_pk_fma_f32 v[10:11], v[16:17], v[106:107], v[10:11] op_sel_hi:[0,1,1]
	v_pk_fma_f32 v[8:9], v[90:91], v[100:101], v[8:9] op_sel_hi:[0,1,1]
	v_mov_b32_e32 v16, v91
	v_pk_fma_f32 v[6:7], v[90:91], v[102:103], v[6:7] op_sel_hi:[0,1,1]
	v_cmp_eq_u32_e32 vcc, 0, v5
	v_pk_fma_f32 v[8:9], v[16:17], v[104:105], v[8:9] op_sel_hi:[0,1,1]
	v_pk_fma_f32 v[6:7], v[16:17], v[106:107], v[6:7] op_sel_hi:[0,1,1]
	v_add_u32_e32 v4, 0x880, v4
	v_add_u32_e32 v3, 32, v3
	s_or_b64 s[0:1], vcc, s[0:1]
	s_andn2_b64 exec, exec, s[0:1]
	s_cbranch_execnz .Lao2_loop
; DI unsigned pk2(float a, float b) { f2_t v = {a, b}; return __builtin_bit_cast(unsigned, __builtin_convertvector(v, bf2_t)); }
; DI float bflo(unsigned w) { return __uint_as_float(w << 16); }
; DI float bfhi(unsigned w) { return __uint_as_float(w & 0xffff0000u); }
; DI float sigmoidf_(float z) { return 1.f / (1.f + ex2(-z * L2E)); }
; DI void hgrn_h3(const Params& p, int l, int item, char* lds) {
;     ...
;   const size_t tok0 = (size_t)b * SEQ + c * 64;
;   const f32x4 og = *(const f32x4*)(p.o_norm_g + l * 256 + hh * 64 + 4 * eblk);
; #pragma unroll
;   for (int i = 0; i < 4; ++i) {
;     float sq = ao[i][0] * ao[i][0] + ao[i][1] * ao[i][1] + ao[i][2] * ao[i][2] + ao[i][3] * ao[i][3];
;     sq += __shfl_xor(sq, 1); sq += __shfl_xor(sq, 2); sq += __shfl_xor(sq, 4); sq += __shfl_xor(sq, 8);
;     const float rs = rsqrtf(sq * (1.f / 64.f) + EPS);
;     const size_t tok = tok0 + 4 * tblk + i;
;     const u32x2 gw = *(const u32x2*)(p.P + tok * PP + C_HG + hh * 64 + 4 * eblk);
;     const float g0 = bflo(gw.x), g1 = bfhi(gw.x), g2 = bflo(gw.y), g3 = bfhi(gw.y);
;     u32x2 w; w.x = pk2(ao[i][0] * rs * og.x * g0 * sigmoidf_(g0), ao[i][1] * rs * og.y * g1 * sigmoidf_(g1));
;     w.y = pk2(ao[i][2] * rs * og.z * g2 * sigmoidf_(g2), ao[i][3] * rs * og.w * g3 * sigmoidf_(g3));
;     *(u32x2*)(p.Y + tok * 1024 + 512 + hh * 64 + 4 * eblk) = w;
;   }
.Lao2_done:
	s_waitcnt lgkmcnt(0)
	s_or_b64 exec, exec, s[0:1]
	v_readlane_b32 s8, v253, 36
	v_lshlrev_b32_e32 v15, 2, v2
	v_readlane_b32 s18, v253, 46
	v_readlane_b32 s19, v253, 47
	v_or3_b32 v24, v31, v15, v24
	v_lshlrev_b32_e32 v4, 2, v14
	v_mov_b64_e32 v[16:17], s[18:19]
	v_mad_u64_u32 v[16:17], s[0:1], v24, s86, v[16:17]
	v_mad_i32_i24 v17, v25, s86, v17
	v_lshl_add_u64 v[16:17], v[16:17], 0, v[0:1]
	v_lshlrev_b32_e32 v14, 1, v14
	v_mov_b32_e32 v15, v1
	v_lshl_add_u64 v[20:21], v[16:17], 0, v[14:15]
	global_load_dwordx2 v[16:17], v[20:21], off offset:2816
	v_lshlrev_b32_e32 v2, 2, v30
	v_mov_b32_e32 v3, v1
	v_lshl_add_u64 v[2:3], s[96:97], 0, v[2:3]
	v_mov_b32_e32 v5, v1
	v_lshl_add_u64 v[2:3], v[2:3], 0, v[4:5]
	global_load_dwordx4 v[2:5], v[2:3], off
	v_pk_mul_f32 v[42:43], v[28:29], v[28:29]
	v_pk_mul_f32 v[40:41], v[26:27], v[26:27]
	v_pk_mul_f32 v[50:51], v[18:19], v[18:19]
	v_mov_b32_e32 v53, v42
	s_mov_b32 s2, 0x3c800000
	s_add_i32 s4, s4, s88
	s_cmpk_gt_i32 s4, 0x7ff
	v_readlane_b32 s9, v253, 37
	v_readlane_b32 s10, v253, 38
	v_readlane_b32 s11, v253, 39
	v_readlane_b32 s12, v253, 40
	v_readlane_b32 s13, v253, 41
	v_readlane_b32 s14, v253, 42
	v_readlane_b32 s15, v253, 43
	v_readlane_b32 s16, v253, 44
	v_readlane_b32 s17, v253, 45
	v_readlane_b32 s20, v253, 48
	v_readlane_b32 s21, v253, 49
	v_readlane_b32 s22, v253, 50
	v_readlane_b32 s23, v253, 51
	s_waitcnt vmcnt(1)
	v_lshlrev_b32_e32 v30, 16, v16
	v_and_b32_e32 v31, 0xffff0000, v16
	v_mul_f32_e32 v16, 0xbfb8aa3b, v30
	v_exp_f32_e32 v32, v16
	v_mul_f32_e32 v16, 0xbfb8aa3b, v31
	v_exp_f32_e32 v33, v16
	s_nop 0
	v_pk_add_f32 v[32:33], v[32:33], 1.0 op_sel_hi:[1,0]
	s_nop 0
	v_div_scale_f32 v16, s[0:1], v33, v33, 1.0
	v_rcp_f32_e32 v34, v16
	s_nop 0
	v_fma_f32 v35, -v16, v34, 1.0
	v_fmac_f32_e32 v34, v35, v34
	v_div_scale_f32 v35, vcc, 1.0, v33, 1.0
	v_mul_f32_e32 v36, v35, v34
	v_fma_f32 v37, -v16, v36, v35
	v_fmac_f32_e32 v36, v37, v34
	v_fma_f32 v16, -v16, v36, v35
	v_div_fmas_f32 v16, v16, v34, v36
	v_div_fixup_f32 v33, v16, v33, 1.0
	v_div_scale_f32 v16, s[0:1], v32, v32, 1.0
	v_rcp_f32_e32 v34, v16
	s_nop 0
	v_fma_f32 v35, -v16, v34, 1.0
	v_fmac_f32_e32 v34, v35, v34
	v_div_scale_f32 v35, vcc, 1.0, v32, 1.0
	v_mul_f32_e32 v36, v35, v34
	v_fma_f32 v37, -v16, v36, v35
	v_fmac_f32_e32 v36, v37, v34
	v_fma_f32 v16, -v16, v36, v35
	v_div_fmas_f32 v16, v16, v34, v36
	v_lshlrev_b32_e32 v34, 16, v17
	v_and_b32_e32 v35, 0xffff0000, v17
	v_div_fixup_f32 v32, v16, v32, 1.0
	v_mul_f32_e32 v16, 0xbfb8aa3b, v34
	v_mul_f32_e32 v17, 0xbfb8aa3b, v35
	v_exp_f32_e32 v16, v16
	v_exp_f32_e32 v17, v17
	s_nop 0
	v_pk_add_f32 v[16:17], v[16:17], 1.0 op_sel_hi:[1,0]
	s_nop 0
	v_div_scale_f32 v36, s[0:1], v17, v17, 1.0
	v_rcp_f32_e32 v37, v36
	s_nop 0
	v_fma_f32 v38, -v36, v37, 1.0
	v_fmac_f32_e32 v37, v38, v37
	v_div_scale_f32 v38, vcc, 1.0, v17, 1.0
	v_mul_f32_e32 v39, v38, v37
	v_fma_f32 v49, -v36, v39, v38
	v_fmac_f32_e32 v39, v49, v37
	v_fma_f32 v36, -v36, v39, v38
	v_div_fmas_f32 v36, v36, v37, v39
	v_div_fixup_f32 v37, v36, v17, 1.0
	v_div_scale_f32 v17, s[0:1], v16, v16, 1.0
	v_rcp_f32_e32 v36, v17
	s_mov_b32 s0, 0x358637bd
	v_fma_f32 v38, -v17, v36, 1.0
	v_fmac_f32_e32 v36, v38, v36
	v_div_scale_f32 v38, vcc, 1.0, v16, 1.0
	v_mul_f32_e32 v39, v38, v36
	v_fma_f32 v49, -v17, v39, v38
	v_fmac_f32_e32 v39, v49, v36
	v_fma_f32 v17, -v17, v39, v38
	v_div_fmas_f32 v17, v17, v36, v39
	v_div_fixup_f32 v36, v17, v16, 1.0
	v_lshlrev_b64 v[16:17], 11, v[24:25]
	v_lshl_add_u64 v[24:25], s[58:59], 0, v[16:17]
	v_lshl_add_u64 v[24:25], v[24:25], 0, v[0:1]
	v_lshl_add_u64 v[38:39], v[24:25], 0, v[14:15]
	v_pk_mul_f32 v[24:25], v[22:23], v[22:23]
	s_nop 0
	v_mov_b32_e32 v52, v24
	v_mov_b32_e32 v42, v25
	v_pk_add_f32 v[24:25], v[52:53], v[42:43]
	v_mov_b32_e32 v42, v50
	v_mov_b32_e32 v43, v40
	v_pk_add_f32 v[24:25], v[42:43], v[24:25]
	v_mov_b32_e32 v40, v51
	v_pk_add_f32 v[24:25], v[40:41], v[24:25]
	ds_bpermute_b32 v41, v159, v25
	ds_bpermute_b32 v40, v159, v24
	s_waitcnt lgkmcnt(0)
	v_pk_add_f32 v[24:25], v[24:25], v[40:41]
	ds_bpermute_b32 v41, v158, v25
	ds_bpermute_b32 v40, v158, v24
	s_waitcnt lgkmcnt(0)
	v_pk_add_f32 v[24:25], v[24:25], v[40:41]
	ds_bpermute_b32 v41, v157, v25
	ds_bpermute_b32 v40, v157, v24
	s_waitcnt lgkmcnt(0)
	v_pk_add_f32 v[24:25], v[24:25], v[40:41]
	ds_bpermute_b32 v41, v156, v25
	ds_bpermute_b32 v40, v156, v24
	s_waitcnt lgkmcnt(0)
	v_pk_add_f32 v[40:41], v[24:25], v[40:41]
	v_mov_b64_e32 v[24:25], s[0:1]
	v_pk_fma_f32 v[40:41], v[40:41], s[2:3], v[24:25] op_sel_hi:[1,0,0]
	s_nop 0
	v_mul_f32_e32 v42, 0x4b800000, v41
	v_cmp_gt_f32_e64 s[0:1], s72, v41
	v_cmp_gt_f32_e32 vcc, s72, v40
	s_nop 0
	v_cndmask_b32_e64 v41, v41, v42, s[0:1]
	v_rsq_f32_e32 v41, v41
	s_nop 0
	v_mul_f32_e32 v42, 0x45800000, v41
	v_cndmask_b32_e64 v42, v41, v42, s[0:1]
	v_pk_mul_f32 v[28:29], v[28:29], v[42:43] op_sel_hi:[1,0]
	v_pk_mul_f32 v[26:27], v[26:27], v[42:43] op_sel_hi:[1,0]
	s_waitcnt vmcnt(0)
	v_pk_mul_f32 v[28:29], v[2:3], v[28:29]
	v_pk_mul_f32 v[26:27], v[4:5], v[26:27]
	v_pk_mul_f32 v[28:29], v[28:29], v[30:31]
	v_pk_mul_f32 v[26:27], v[26:27], v[34:35]
	v_pk_mul_f32 v[28:29], v[32:33], v[28:29]
	v_pk_mul_f32 v[26:27], v[36:37], v[26:27]
	v_cvt_pk_bf16_f32 v28, v28, v29
	v_cvt_pk_bf16_f32 v29, v26, v27
	v_mul_f32_e32 v26, 0x4b800000, v40
	v_cndmask_b32_e32 v26, v40, v26, vcc
	v_rsq_f32_e32 v26, v26
	s_movk_i32 s0, 0x1000
	global_store_dwordx2 v[38:39], v[28:29], off offset:1024
	v_mul_f32_e32 v27, 0x45800000, v26
	v_cndmask_b32_e32 v26, v26, v27, vcc
	v_add_co_u32_e32 v28, vcc, s0, v20
	s_nop 1
	v_addc_co_u32_e32 v29, vcc, 0, v21, vcc
	global_load_dwordx2 v[28:29], v[28:29], off offset:3648
	s_waitcnt vmcnt(0)
; DI unsigned pk2(float a, float b) { f2_t v = {a, b}; return __builtin_bit_cast(unsigned, __builtin_convertvector(v, bf2_t)); }
; DI float bflo(unsigned w) { return __uint_as_float(w << 16); }
; DI float bfhi(unsigned w) { return __uint_as_float(w & 0xffff0000u); }
; DI float sigmoidf_(float z) { return 1.f / (1.f + ex2(-z * L2E)); }
; DI void hgrn_h3(const Params& p, int l, int item, char* lds) {
;     ...
; #pragma unroll
;   for (int i = 0; i < 4; ++i) {
;     float sq = ao[i][0] * ao[i][0] + ao[i][1] * ao[i][1] + ao[i][2] * ao[i][2] + ao[i][3] * ao[i][3];
;     sq += __shfl_xor(sq, 1); sq += __shfl_xor(sq, 2); sq += __shfl_xor(sq, 4); sq += __shfl_xor(sq, 8);
;     const float rs = rsqrtf(sq * (1.f / 64.f) + EPS);
;     const size_t tok = tok0 + 4 * tblk + i;
;     const u32x2 gw = *(const u32x2*)(p.P + tok * PP + C_HG + hh * 64 + 4 * eblk);
;     const float g0 = bflo(gw.x), g1 = bfhi(gw.x), g2 = bflo(gw.y), g3 = bfhi(gw.y);
;     u32x2 w; w.x = pk2(ao[i][0] * rs * og.x * g0 * sigmoidf_(g0), ao[i][1] * rs * og.y * g1 * sigmoidf_(g1));
;     w.y = pk2(ao[i][2] * rs * og.z * g2 * sigmoidf_(g2), ao[i][3] * rs * og.w * g3 * sigmoidf_(g3));
;     *(u32x2*)(p.Y + tok * 1024 + 512 + hh * 64 + 4 * eblk) = w;
;   }
	v_lshlrev_b32_e32 v30, 16, v28
	v_and_b32_e32 v31, 0xffff0000, v28
	v_mul_f32_e32 v27, 0xbfb8aa3b, v30
	v_exp_f32_e32 v32, v27
	v_pk_mul_f32 v[22:23], v[22:23], v[26:27] op_sel_hi:[1,0]
	v_mul_f32_e32 v27, 0xbfb8aa3b, v31
	v_exp_f32_e32 v33, v27
	v_pk_mul_f32 v[22:23], v[2:3], v[22:23]
	s_nop 0
	v_pk_mul_f32 v[22:23], v[22:23], v[30:31]
	v_pk_add_f32 v[30:31], v[32:33], 1.0 op_sel_hi:[1,0]
	s_nop 0
	v_div_scale_f32 v27, s[0:1], v31, v31, 1.0
	v_rcp_f32_e32 v28, v27
	s_nop 0
	v_fma_f32 v32, -v27, v28, 1.0
	v_fmac_f32_e32 v28, v32, v28
	v_div_scale_f32 v32, vcc, 1.0, v31, 1.0
	v_mul_f32_e32 v33, v32, v28
	v_fma_f32 v34, -v27, v33, v32
	v_fmac_f32_e32 v33, v34, v28
	v_fma_f32 v27, -v27, v33, v32
	v_div_fmas_f32 v27, v27, v28, v33
	v_div_fixup_f32 v31, v27, v31, 1.0
	v_div_scale_f32 v27, s[0:1], v30, v30, 1.0
	v_rcp_f32_e32 v28, v27
	s_nop 0
	v_fma_f32 v32, -v27, v28, 1.0
	v_fmac_f32_e32 v28, v32, v28
	v_div_scale_f32 v32, vcc, 1.0, v30, 1.0
	v_mul_f32_e32 v33, v32, v28
	v_fma_f32 v34, -v27, v33, v32
	v_fmac_f32_e32 v33, v34, v28
	v_fma_f32 v27, -v27, v33, v32
	v_div_fmas_f32 v27, v27, v28, v33
	v_div_fixup_f32 v30, v27, v30, 1.0
	v_pk_mul_f32 v[22:23], v[30:31], v[22:23]
	v_lshlrev_b32_e32 v28, 16, v29
	v_cvt_pk_bf16_f32 v22, v22, v23
	v_and_b32_e32 v29, 0xffff0000, v29
	v_mul_f32_e32 v23, 0xbfb8aa3b, v28
	v_exp_f32_e32 v30, v23
	v_mul_f32_e32 v23, 0xbfb8aa3b, v29
	v_exp_f32_e32 v31, v23
	v_pk_mul_f32 v[18:19], v[18:19], v[26:27] op_sel_hi:[1,0]
	v_pk_mul_f32 v[34:35], v[12:13], v[12:13]
	v_pk_mul_f32 v[18:19], v[4:5], v[18:19]
	v_pk_add_f32 v[26:27], v[30:31], 1.0 op_sel_hi:[1,0]
	v_pk_mul_f32 v[18:19], v[18:19], v[28:29]
	v_div_scale_f32 v23, s[0:1], v27, v27, 1.0
	v_rcp_f32_e32 v28, v23
	v_pk_mul_f32 v[32:33], v[10:11], v[10:11]
	v_mov_b32_e32 v41, v34
	v_fma_f32 v29, -v23, v28, 1.0
	v_fmac_f32_e32 v28, v29, v28
	v_div_scale_f32 v29, vcc, 1.0, v27, 1.0
	v_mul_f32_e32 v30, v29, v28
	v_fma_f32 v31, -v23, v30, v29
	v_fmac_f32_e32 v30, v31, v28
	v_fma_f32 v23, -v23, v30, v29
	v_div_fmas_f32 v23, v23, v28, v30
	v_div_fixup_f32 v27, v23, v27, 1.0
	v_div_scale_f32 v23, s[0:1], v26, v26, 1.0
	v_rcp_f32_e32 v28, v23
	s_movk_i32 s0, 0x3000
	v_fma_f32 v29, -v23, v28, 1.0
	v_fmac_f32_e32 v28, v29, v28
	v_div_scale_f32 v29, vcc, 1.0, v26, 1.0
	v_mul_f32_e32 v30, v29, v28
	v_fma_f32 v31, -v23, v30, v29
	v_fmac_f32_e32 v30, v31, v28
	v_fma_f32 v23, -v23, v30, v29
	v_div_fmas_f32 v23, v23, v28, v30
	v_div_fixup_f32 v26, v23, v26, 1.0
	v_pk_mul_f32 v[18:19], v[26:27], v[18:19]
	s_nop 0
	v_cvt_pk_bf16_f32 v23, v18, v19
	v_or_b32_e32 v18, 0x800, v16
	v_mov_b32_e32 v19, v17
	v_lshl_add_u64 v[18:19], s[58:59], 0, v[18:19]
	v_lshl_add_u64 v[18:19], v[18:19], 0, v[0:1]
	v_lshl_add_u64 v[18:19], v[18:19], 0, v[14:15]
	global_store_dwordx2 v[18:19], v[22:23], off offset:1024
	v_add_co_u32_e32 v18, vcc, s0, v20
	s_nop 1
	v_addc_co_u32_e32 v19, vcc, 0, v21, vcc
	global_load_dwordx2 v[26:27], v[18:19], off offset:384
	s_waitcnt vmcnt(0)
	v_lshlrev_b32_e32 v18, 16, v26
	v_and_b32_e32 v19, 0xffff0000, v26
	v_mul_f32_e32 v22, 0xbfb8aa3b, v18
	v_mul_f32_e32 v23, 0xbfb8aa3b, v19
	v_exp_f32_e32 v22, v22
	v_exp_f32_e32 v23, v23
	s_nop 0
	v_pk_add_f32 v[22:23], v[22:23], 1.0 op_sel_hi:[1,0]
	s_nop 0
	v_div_scale_f32 v26, s[0:1], v23, v23, 1.0
	v_rcp_f32_e32 v28, v26
	s_nop 0
	v_fma_f32 v29, -v26, v28, 1.0
	v_fmac_f32_e32 v28, v29, v28
	v_div_scale_f32 v29, vcc, 1.0, v23, 1.0
	v_mul_f32_e32 v30, v29, v28
	v_fma_f32 v31, -v26, v30, v29
	v_fmac_f32_e32 v30, v31, v28
	v_fma_f32 v26, -v26, v30, v29
	v_div_fmas_f32 v26, v26, v28, v30
	v_div_fixup_f32 v23, v26, v23, 1.0
	v_div_scale_f32 v26, s[0:1], v22, v22, 1.0
	v_rcp_f32_e32 v28, v26
	s_nop 0
	v_fma_f32 v29, -v26, v28, 1.0
	v_fmac_f32_e32 v28, v29, v28
	v_div_scale_f32 v29, vcc, 1.0, v22, 1.0
	v_mul_f32_e32 v30, v29, v28
	v_fma_f32 v31, -v26, v30, v29
	v_fmac_f32_e32 v30, v31, v28
	v_fma_f32 v26, -v26, v30, v29
	v_div_fmas_f32 v26, v26, v28, v30
	v_div_fixup_f32 v22, v26, v22, 1.0
	v_lshlrev_b32_e32 v26, 16, v27
	v_and_b32_e32 v27, 0xffff0000, v27
	v_mul_f32_e32 v28, 0xbfb8aa3b, v26
	v_mul_f32_e32 v29, 0xbfb8aa3b, v27
	v_exp_f32_e32 v28, v28
	v_exp_f32_e32 v29, v29
	s_nop 0
	v_pk_add_f32 v[28:29], v[28:29], 1.0 op_sel_hi:[1,0]
	s_nop 0
	v_div_scale_f32 v30, s[0:1], v29, v29, 1.0
	v_rcp_f32_e32 v31, v30
	s_nop 0
	v_fma_f32 v36, -v30, v31, 1.0
	v_fmac_f32_e32 v31, v36, v31
	v_div_scale_f32 v36, vcc, 1.0, v29, 1.0
	v_mul_f32_e32 v37, v36, v31
	v_fma_f32 v38, -v30, v37, v36
	v_fmac_f32_e32 v37, v38, v31
	v_fma_f32 v30, -v30, v37, v36
	v_div_fmas_f32 v30, v30, v31, v37
	v_div_fixup_f32 v29, v30, v29, 1.0
	v_div_scale_f32 v30, s[0:1], v28, v28, 1.0
	v_rcp_f32_e32 v31, v30
	s_nop 0
	v_fma_f32 v36, -v30, v31, 1.0
	v_fmac_f32_e32 v31, v36, v31
	v_div_scale_f32 v36, vcc, 1.0, v28, 1.0
	v_mul_f32_e32 v37, v36, v31
	v_fma_f32 v38, -v30, v37, v36
	v_fmac_f32_e32 v37, v38, v31
	v_fma_f32 v30, -v30, v37, v36
	v_div_fmas_f32 v30, v30, v31, v37
	v_pk_mul_f32 v[36:37], v[8:9], v[8:9]
	v_pk_mul_f32 v[38:39], v[6:7], v[6:7]
	v_mov_b32_e32 v40, v36
	v_mov_b32_e32 v34, v37
	v_pk_add_f32 v[34:35], v[40:41], v[34:35]
	v_mov_b32_e32 v36, v38
	v_mov_b32_e32 v37, v32
	v_pk_add_f32 v[34:35], v[36:37], v[34:35]
	v_mov_b32_e32 v32, v39
	v_pk_add_f32 v[32:33], v[32:33], v[34:35]
	ds_bpermute_b32 v35, v159, v33
	ds_bpermute_b32 v34, v159, v32
	v_div_fixup_f32 v28, v30, v28, 1.0
	v_or_b32_e32 v30, 0x1000, v16
	v_mov_b32_e32 v31, v17
	v_lshl_add_u64 v[30:31], s[58:59], 0, v[30:31]
	s_waitcnt lgkmcnt(0)
; DI unsigned pk2(float a, float b) { f2_t v = {a, b}; return __builtin_bit_cast(unsigned, __builtin_convertvector(v, bf2_t)); }
; DI float bflo(unsigned w) { return __uint_as_float(w << 16); }
; DI float bfhi(unsigned w) { return __uint_as_float(w & 0xffff0000u); }
; DI float sigmoidf_(float z) { return 1.f / (1.f + ex2(-z * L2E)); }
; DI void hgrn_h3(const Params& p, int l, int item, char* lds) {
;     ...
; #pragma unroll
;   for (int i = 0; i < 4; ++i) {
;     float sq = ao[i][0] * ao[i][0] + ao[i][1] * ao[i][1] + ao[i][2] * ao[i][2] + ao[i][3] * ao[i][3];
;     sq += __shfl_xor(sq, 1); sq += __shfl_xor(sq, 2); sq += __shfl_xor(sq, 4); sq += __shfl_xor(sq, 8);
;     const float rs = rsqrtf(sq * (1.f / 64.f) + EPS);
;     const size_t tok = tok0 + 4 * tblk + i;
;     const u32x2 gw = *(const u32x2*)(p.P + tok * PP + C_HG + hh * 64 + 4 * eblk);
;     const float g0 = bflo(gw.x), g1 = bfhi(gw.x), g2 = bflo(gw.y), g3 = bfhi(gw.y);
;     u32x2 w; w.x = pk2(ao[i][0] * rs * og.x * g0 * sigmoidf_(g0), ao[i][1] * rs * og.y * g1 * sigmoidf_(g1));
;     w.y = pk2(ao[i][2] * rs * og.z * g2 * sigmoidf_(g2), ao[i][3] * rs * og.w * g3 * sigmoidf_(g3));
;     *(u32x2*)(p.Y + tok * 1024 + 512 + hh * 64 + 4 * eblk) = w;
;   }
	v_pk_add_f32 v[32:33], v[32:33], v[34:35]
	ds_bpermute_b32 v35, v158, v33
	ds_bpermute_b32 v34, v158, v32
	v_lshl_add_u64 v[30:31], v[30:31], 0, v[0:1]
	v_lshl_add_u64 v[30:31], v[30:31], 0, v[14:15]
	v_or_b32_e32 v16, 0x1800, v16
	s_waitcnt lgkmcnt(0)
	v_pk_add_f32 v[32:33], v[32:33], v[34:35]
	ds_bpermute_b32 v35, v157, v33
	ds_bpermute_b32 v34, v157, v32
	s_waitcnt lgkmcnt(0)
	v_pk_add_f32 v[32:33], v[32:33], v[34:35]
	ds_bpermute_b32 v35, v156, v33
	ds_bpermute_b32 v34, v156, v32
	s_waitcnt lgkmcnt(0)
	v_pk_add_f32 v[32:33], v[32:33], v[34:35]
	s_nop 0
	v_pk_fma_f32 v[24:25], v[32:33], s[2:3], v[24:25] op_sel_hi:[1,0,0]
	s_nop 0
	v_mul_f32_e32 v32, 0x4b800000, v25
	v_cmp_gt_f32_e64 s[0:1], s72, v25
	v_cmp_gt_f32_e32 vcc, s72, v24
	s_nop 0
	v_cndmask_b32_e64 v25, v25, v32, s[0:1]
	v_rsq_f32_e32 v25, v25
	s_nop 0
	v_mul_f32_e32 v32, 0x45800000, v25
	v_cndmask_b32_e64 v32, v25, v32, s[0:1]
	v_pk_mul_f32 v[12:13], v[12:13], v[32:33] op_sel_hi:[1,0]
	v_pk_mul_f32 v[10:11], v[10:11], v[32:33] op_sel_hi:[1,0]
	v_pk_mul_f32 v[12:13], v[2:3], v[12:13]
	v_pk_mul_f32 v[10:11], v[4:5], v[10:11]
	v_pk_mul_f32 v[12:13], v[12:13], v[18:19]
	v_pk_mul_f32 v[10:11], v[10:11], v[26:27]
	v_pk_mul_f32 v[12:13], v[22:23], v[12:13]
	v_pk_mul_f32 v[10:11], v[28:29], v[10:11]
	v_cvt_pk_bf16_f32 v12, v12, v13
	v_cvt_pk_bf16_f32 v13, v10, v11
	v_mul_f32_e32 v10, 0x4b800000, v24
	v_cndmask_b32_e32 v10, v24, v10, vcc
	v_rsq_f32_e32 v10, v10
	s_movk_i32 s0, 0x4000
	global_store_dwordx2 v[30:31], v[12:13], off offset:1024
	v_mul_f32_e32 v11, 0x45800000, v10
	v_cndmask_b32_e32 v10, v10, v11, vcc
	v_add_co_u32_e32 v12, vcc, s0, v20
	s_nop 1
	v_addc_co_u32_e32 v13, vcc, 0, v21, vcc
	global_load_dwordx2 v[12:13], v[12:13], off offset:1216
	s_waitcnt vmcnt(0)
	v_lshlrev_b32_e32 v18, 16, v12
	v_mul_f32_e32 v11, 0xbfb8aa3b, v18
	v_and_b32_e32 v19, 0xffff0000, v12
	v_pk_mul_f32 v[8:9], v[8:9], v[10:11] op_sel_hi:[1,0]
	v_exp_f32_e32 v20, v11
	v_pk_mul_f32 v[2:3], v[2:3], v[8:9]
	v_mul_f32_e32 v8, 0xbfb8aa3b, v19
	v_exp_f32_e32 v21, v8
	v_pk_mul_f32 v[2:3], v[2:3], v[18:19]
	v_pk_add_f32 v[8:9], v[20:21], 1.0 op_sel_hi:[1,0]
	s_nop 0
	v_div_scale_f32 v11, s[0:1], v9, v9, 1.0
	v_rcp_f32_e32 v12, v11
	s_nop 0
	v_fma_f32 v18, -v11, v12, 1.0
	v_fmac_f32_e32 v12, v18, v12
	v_div_scale_f32 v18, vcc, 1.0, v9, 1.0
	v_mul_f32_e32 v19, v18, v12
	v_fma_f32 v20, -v11, v19, v18
	v_fmac_f32_e32 v19, v20, v12
	v_fma_f32 v11, -v11, v19, v18
	v_div_fmas_f32 v11, v11, v12, v19
	v_div_fixup_f32 v9, v11, v9, 1.0
	v_div_scale_f32 v11, s[0:1], v8, v8, 1.0
	v_rcp_f32_e32 v12, v11
	s_nop 0
	v_fma_f32 v18, -v11, v12, 1.0
	v_fmac_f32_e32 v12, v18, v12
	v_div_scale_f32 v18, vcc, 1.0, v8, 1.0
	v_mul_f32_e32 v19, v18, v12
	v_fma_f32 v20, -v11, v19, v18
	v_fmac_f32_e32 v19, v20, v12
	v_fma_f32 v11, -v11, v19, v18
	v_div_fmas_f32 v11, v11, v12, v19
	v_div_fixup_f32 v8, v11, v8, 1.0
	v_pk_mul_f32 v[2:3], v[8:9], v[2:3]
	v_lshlrev_b32_e32 v8, 16, v13
	v_cvt_pk_bf16_f32 v2, v2, v3
	v_and_b32_e32 v9, 0xffff0000, v13
	v_mul_f32_e32 v3, 0xbfb8aa3b, v8
	v_exp_f32_e32 v12, v3
	v_mul_f32_e32 v3, 0xbfb8aa3b, v9
	v_exp_f32_e32 v13, v3
	v_pk_mul_f32 v[6:7], v[6:7], v[10:11] op_sel_hi:[1,0]
	s_nop 0
	v_pk_mul_f32 v[4:5], v[4:5], v[6:7]
	v_pk_add_f32 v[6:7], v[12:13], 1.0 op_sel_hi:[1,0]
	v_pk_mul_f32 v[4:5], v[4:5], v[8:9]
	v_div_scale_f32 v3, s[0:1], v7, v7, 1.0
	v_rcp_f32_e32 v8, v3
	s_nop 0
	v_fma_f32 v9, -v3, v8, 1.0
	v_fmac_f32_e32 v8, v9, v8
	v_div_scale_f32 v9, vcc, 1.0, v7, 1.0
	v_mul_f32_e32 v10, v9, v8
	v_fma_f32 v11, -v3, v10, v9
	v_fmac_f32_e32 v10, v11, v8
	v_fma_f32 v3, -v3, v10, v9
	v_div_fmas_f32 v3, v3, v8, v10
	v_div_fixup_f32 v7, v3, v7, 1.0
	v_div_scale_f32 v3, s[0:1], v6, v6, 1.0
	v_rcp_f32_e32 v8, v3
	s_nop 0
	v_fma_f32 v9, -v3, v8, 1.0
	v_fmac_f32_e32 v8, v9, v8
	v_div_scale_f32 v9, vcc, 1.0, v6, 1.0
	v_mul_f32_e32 v10, v9, v8
	v_fma_f32 v11, -v3, v10, v9
	v_fmac_f32_e32 v10, v11, v8
	v_fma_f32 v3, -v3, v10, v9
	v_div_fmas_f32 v3, v3, v8, v10
	v_div_fixup_f32 v6, v3, v6, 1.0
	v_pk_mul_f32 v[4:5], v[6:7], v[4:5]
	s_nop 0
	v_cvt_pk_bf16_f32 v3, v4, v5
	v_lshl_add_u64 v[4:5], s[58:59], 0, v[16:17]
	v_lshl_add_u64 v[4:5], v[4:5], 0, v[0:1]
	v_lshl_add_u64 v[4:5], v[4:5], 0, v[14:15]
	global_store_dwordx2 v[4:5], v[2:3], off offset:1024
	s_cbranch_scc0 .LBB0_547
